# v90 + gMLP V^T fragment LDS reads issued ahead into private registers
# baseline (speedup 1.0000x reference)
; #define LAS __attribute__((address_space(3)))
; __device__ __forceinline__ unsigned pk2(float lo, float hi) { return pg8::cvt_pk_bf16(lo, hi); }
; __device__ __forceinline__ void gmlp_unit(const bf16* proj, unsigned char* ws, LAS unsigned char* lds, int gu) {
;     ...
;     for (int p = 0; p < 4; ++p) {
;         const float mu = stv[p][0] * (1.0f / 1024.0f), var = fmaxf(stv[p][1] * (1.0f / 1024.0f) - mu * mu, 0.f), rstd = 1.0f / sqrtf(var + pg8::EPSN);
;         float v[8];
;         v[0] = bflo(raw[p].x); v[1] = bfhi(raw[p].x); v[2] = bflo(raw[p].y); v[3] = bfhi(raw[p].y); v[4] = bflo(raw[p].z); v[5] = bfhi(raw[p].z); v[6] = bflo(raw[p].w); v[7] = bfhi(raw[p].w);
; #pragma unroll
;         for (int e = 0; e < 4; ++e) { v[e] = (v[e] - mu) * rstd * g0[e] + b0[e]; v[4 + e] = (v[4 + e] - mu) * rstd * g1[e] + b1[e]; }
;         v4u o; o.x = pk2(v[0], v[1]); o.y = pk2(v[2], v[3]); o.z = pk2(v[4], v[5]); o.w = pk2(v[6], v[7]);
;         *(LAS v4u*)(VN + (r0 + 32 * p) * V_STRIDE + c * 16) = o;
.Lgm_nobar:
	s_nop 0
	v_cndmask_b32_e64 v79, v80, v81, s[2:3]
	v_mul_f32_e32 v80, 0x37800000, v79
	v_cndmask_b32_e32 v79, v79, v80, vcc
	v_cmp_class_f32_e32 vcc, v75, v166
	v_fma_f32 v59, -v58, v58, v59
	s_nop 0
	v_cndmask_b32_e32 v75, v79, v75, vcc
	v_div_scale_f32 v79, s[0:1], v75, v75, 1.0
	v_rcp_f32_e32 v80, v79
	v_max_f32_e32 v59, 0, v59
	v_add_f32_e32 v59, 0x358637bd, v59
	v_fma_f32 v81, -v79, v80, 1.0
	v_fmac_f32_e32 v80, v81, v80
	v_div_scale_f32 v81, vcc, 1.0, v75, 1.0
	v_mul_f32_e32 v82, v81, v80
	v_fma_f32 v83, -v79, v82, v81
	v_fmac_f32_e32 v82, v83, v80
	v_fma_f32 v79, -v79, v82, v81
	v_div_fmas_f32 v79, v79, v80, v82
	v_div_fixup_f32 v75, v79, v75, 1.0
	s_waitcnt vmcnt(20)
	v_lshlrev_b32_e32 v79, 16, v62
	v_and_b32_e32 v62, 0xffff0000, v62
	v_lshlrev_b32_e32 v80, 16, v63
	v_and_b32_e32 v63, 0xffff0000, v63
	v_lshlrev_b32_e32 v81, 16, v64
	v_and_b32_e32 v64, 0xffff0000, v64
	v_lshlrev_b32_e32 v82, 16, v65
	v_and_b32_e32 v65, 0xffff0000, v65
	v_sub_f32_e32 v79, v79, v74
	v_sub_f32_e32 v81, v81, v74
	v_sub_f32_e32 v62, v62, v74
	v_sub_f32_e32 v64, v64, v74
	v_sub_f32_e32 v80, v80, v74
	v_sub_f32_e32 v82, v82, v74
	v_sub_f32_e32 v63, v63, v74
	v_sub_f32_e32 v65, v65, v74
	v_mul_f32_e32 v74, 0x4f800000, v71
	v_cmp_gt_f32_e32 vcc, s61, v71
	v_mul_f32_e32 v79, v79, v75
	v_mul_f32_e32 v62, v62, v75
	v_cndmask_b32_e32 v71, v71, v74, vcc
	v_sqrt_f32_e32 v74, v71
	s_waitcnt vmcnt(13)
	v_fma_f32 v79, v28, v79, v24
	v_mul_f32_e32 v81, v81, v75
	v_fma_f32 v62, v29, v62, v25
	v_mul_f32_e32 v64, v64, v75
	v_mul_f32_e32 v80, v80, v75
	v_mul_f32_e32 v82, v82, v75
	v_mul_f32_e32 v63, v63, v75
	v_mul_f32_e32 v65, v65, v75
	v_add_u32_e32 v75, -1, v74
	v_cvt_pk_bf16_f32 v62, v79, v62
	v_fma_f32 v79, -v75, v74, v71
	v_cmp_ge_f32_e64 s[2:3], 0, v79
	v_add_u32_e32 v79, 1, v74
	v_fma_f32 v64, v17, v64, v21
	v_cndmask_b32_e64 v75, v74, v75, s[2:3]
	v_fma_f32 v74, -v79, v74, v71
	v_cmp_lt_f32_e64 s[2:3], 0, v74
	v_fma_f32 v63, v31, v63, v27
	v_fma_f32 v65, v19, v65, v23
	v_cndmask_b32_e64 v74, v75, v79, s[2:3]
	v_mul_f32_e32 v75, 0x37800000, v74
	v_cndmask_b32_e32 v74, v74, v75, vcc
	v_cmp_class_f32_e32 vcc, v71, v166
	v_fma_f32 v81, v16, v81, v20
	v_fma_f32 v80, v30, v80, v26
	v_cndmask_b32_e32 v71, v74, v71, vcc
	v_div_scale_f32 v74, s[0:1], v71, v71, 1.0
	v_rcp_f32_e32 v75, v74
	v_fma_f32 v82, v18, v82, v22
	v_cvt_pk_bf16_f32 v63, v80, v63
	v_cvt_pk_bf16_f32 v64, v81, v64
	v_cvt_pk_bf16_f32 v65, v82, v65
	ds_write_b128 v76, v[62:65]
	v_fma_f32 v62, -v74, v75, 1.0
	v_fmac_f32_e32 v75, v62, v75
	v_div_scale_f32 v62, vcc, 1.0, v71, 1.0
	v_mul_f32_e32 v63, v62, v75
	v_fma_f32 v64, -v74, v63, v62
	v_fmac_f32_e32 v63, v64, v75
	v_fma_f32 v62, -v74, v63, v62
	v_div_fmas_f32 v62, v62, v75, v63
	v_lshlrev_b32_e32 v63, 16, v66
	v_and_b32_e32 v64, 0xffff0000, v66
	v_lshlrev_b32_e32 v65, 16, v67
	v_and_b32_e32 v66, 0xffff0000, v67
	v_lshlrev_b32_e32 v67, 16, v68
	v_div_fixup_f32 v62, v62, v71, 1.0
	v_sub_f32_e32 v67, v67, v70
	v_and_b32_e32 v68, 0xffff0000, v68
	v_mul_f32_e32 v67, v67, v62
	v_fma_f32 v74, v16, v67, v20
	v_sub_f32_e32 v67, v68, v70
	v_lshlrev_b32_e32 v71, 16, v69
	v_mul_f32_e32 v67, v67, v62
	v_sub_f32_e32 v66, v66, v70
	v_and_b32_e32 v69, 0xffff0000, v69
	v_fma_f32 v68, v17, v67, v21
	v_sub_f32_e32 v67, v71, v70
	v_mul_f32_e32 v66, v66, v62
	v_sub_f32_e32 v63, v63, v70
	v_sub_f32_e32 v64, v64, v70
	v_sub_f32_e32 v65, v65, v70
	v_mul_f32_e32 v67, v67, v62
	v_fma_f32 v75, v31, v66, v27
	v_sub_f32_e32 v66, v69, v70
	v_mul_f32_e32 v63, v63, v62
	v_mul_f32_e32 v64, v64, v62
	v_mul_f32_e32 v65, v65, v62
	v_fma_f32 v71, v18, v67, v22
	v_mul_f32_e32 v62, v66, v62
	v_pk_mul_f32 v[66:67], v[72:73], s[46:47] op_sel_hi:[1,0]
	v_fma_f32 v64, v29, v64, v25
	v_fma_f32 v67, -v66, v66, v67
	v_max_f32_e32 v67, 0, v67
	v_add_f32_e32 v67, 0x358637bd, v67
	v_mul_f32_e32 v69, 0x4f800000, v67
	v_cmp_gt_f32_e32 vcc, s61, v67
	v_fma_f32 v63, v28, v63, v24
	v_fma_f32 v65, v30, v65, v26
	v_cndmask_b32_e32 v67, v67, v69, vcc
	v_sqrt_f32_e32 v69, v67
	v_fma_f32 v70, v19, v62, v23
	v_cvt_pk_bf16_f32 v62, v63, v64
	v_cvt_pk_bf16_f32 v63, v65, v75
	v_add_u32_e32 v64, -1, v69
	v_fma_f32 v65, -v64, v69, v67
	v_cmp_ge_f32_e64 s[2:3], 0, v65
	v_add_u32_e32 v65, 1, v69
	s_nop 0
	v_cndmask_b32_e64 v64, v69, v64, s[2:3]
	v_fma_f32 v69, -v65, v69, v67
	v_cmp_lt_f32_e64 s[2:3], 0, v69
	s_nop 1
	v_cndmask_b32_e64 v64, v64, v65, s[2:3]
	v_mul_f32_e32 v65, 0x37800000, v64
	v_cndmask_b32_e32 v64, v64, v65, vcc
	v_cmp_class_f32_e32 vcc, v67, v166
	s_nop 1
	v_cndmask_b32_e32 v67, v64, v67, vcc
	v_div_scale_f32 v69, s[0:1], v67, v67, 1.0
	v_rcp_f32_e32 v72, v69
	v_cvt_pk_bf16_f32 v64, v74, v68
	v_cvt_pk_bf16_f32 v65, v71, v70
	ds_write_b128 v76, v[62:65] offset:9216
	v_fma_f32 v62, -v69, v72, 1.0
	v_fmac_f32_e32 v72, v62, v72
	v_div_scale_f32 v62, vcc, 1.0, v67, 1.0
	v_mul_f32_e32 v63, v62, v72
	v_fma_f32 v64, -v69, v63, v62
	v_fmac_f32_e32 v63, v64, v72
	v_fma_f32 v62, -v69, v63, v62
	v_div_fmas_f32 v62, v62, v72, v63
	v_div_fixup_f32 v62, v62, v67, 1.0
	v_lshlrev_b32_e32 v63, 16, v36
	v_and_b32_e32 v36, 0xffff0000, v36
	v_lshlrev_b32_e32 v64, 16, v37
	v_and_b32_e32 v37, 0xffff0000, v37
	v_lshlrev_b32_e32 v65, 16, v38
	v_and_b32_e32 v38, 0xffff0000, v38
	v_lshlrev_b32_e32 v67, 16, v39
	v_and_b32_e32 v39, 0xffff0000, v39
	v_sub_f32_e32 v63, v63, v66
	v_sub_f32_e32 v65, v65, v66
	v_sub_f32_e32 v36, v36, v66
	v_sub_f32_e32 v38, v38, v66
	v_sub_f32_e32 v64, v64, v66
	v_sub_f32_e32 v67, v67, v66
	v_sub_f32_e32 v37, v37, v66
	v_sub_f32_e32 v39, v39, v66
	v_mul_f32_e32 v63, v63, v62
	v_mul_f32_e32 v65, v65, v62
	v_mul_f32_e32 v36, v36, v62
	v_mul_f32_e32 v38, v38, v62
	v_mul_f32_e32 v64, v64, v62
; #define LAS __attribute__((address_space(3)))
; __device__ __forceinline__ unsigned pk2(float lo, float hi) { return pg8::cvt_pk_bf16(lo, hi); }
; __device__ __forceinline__ void gmlp_unit(const bf16* proj, unsigned char* ws, LAS unsigned char* lds, int gu) {
;     ...
;     for (int p = 0; p < 4; ++p) {
;         const float mu = stv[p][0] * (1.0f / 1024.0f), var = fmaxf(stv[p][1] * (1.0f / 1024.0f) - mu * mu, 0.f), rstd = 1.0f / sqrtf(var + pg8::EPSN);
;         float v[8];
;         v[0] = bflo(raw[p].x); v[1] = bfhi(raw[p].x); v[2] = bflo(raw[p].y); v[3] = bfhi(raw[p].y); v[4] = bflo(raw[p].z); v[5] = bfhi(raw[p].z); v[6] = bflo(raw[p].w); v[7] = bfhi(raw[p].w);
; #pragma unroll
;         for (int e = 0; e < 4; ++e) { v[e] = (v[e] - mu) * rstd * g0[e] + b0[e]; v[4 + e] = (v[4 + e] - mu) * rstd * g1[e] + b1[e]; }
;         v4u o; o.x = pk2(v[0], v[1]); o.y = pk2(v[2], v[3]); o.z = pk2(v[4], v[5]); o.w = pk2(v[6], v[7]);
;         *(LAS v4u*)(VN + (r0 + 32 * p) * V_STRIDE + c * 16) = o;
;     }
;     __syncthreads();
;     f32x4 acc[8];
; #pragma unroll
;     for (int ct = 0; ct < 8; ++ct) {
;         acc[ct] = (f32x4){0.f, 0.f, 0.f, 0.f};
; #pragma unroll
;         for (int s = 0; s < 4; ++s) {
;             const LAS unsigned char* p0 = VN + (32 * s + 8 * fq + (fr >> 2)) * V_STRIDE + (16 * ct + 4 * (fr & 3)) * 2;
;             const bf16x8 vf = tr_frag(p0, p0 + 4 * V_STRIDE);
;             acc[ct] = __builtin_amdgcn_mfma_f32_16x16x32_bf16(vf, wf[s], acc[ct], 0, 0, 0);
;         }
;     }
	v_mul_f32_e32 v67, v67, v62
	v_mul_f32_e32 v37, v37, v62
	v_mul_f32_e32 v39, v39, v62
	v_mul_f32_e32 v62, 0x4f800000, v59
	v_cmp_gt_f32_e32 vcc, s61, v59
	v_fma_f32 v63, v28, v63, v24
	v_fma_f32 v36, v29, v36, v25
	v_cndmask_b32_e32 v59, v59, v62, vcc
	v_sqrt_f32_e32 v62, v59
	v_fma_f32 v64, v30, v64, v26
	v_fma_f32 v37, v31, v37, v27
	v_cvt_pk_bf16_f32 v36, v63, v36
	v_add_u32_e32 v63, -1, v62
	v_cvt_pk_bf16_f32 v37, v64, v37
	v_fma_f32 v64, -v63, v62, v59
	v_cmp_ge_f32_e64 s[2:3], 0, v64
	v_add_u32_e32 v64, 1, v62
	v_fma_f32 v38, v17, v38, v21
	v_cndmask_b32_e64 v63, v62, v63, s[2:3]
	v_fma_f32 v62, -v64, v62, v59
	v_cmp_lt_f32_e64 s[2:3], 0, v62
	v_fma_f32 v39, v19, v39, v23
	v_fma_f32 v65, v16, v65, v20
	v_cndmask_b32_e64 v62, v63, v64, s[2:3]
	v_mul_f32_e32 v63, 0x37800000, v62
	v_cndmask_b32_e32 v62, v62, v63, vcc
	v_cmp_class_f32_e32 vcc, v59, v166
	v_fma_f32 v67, v18, v67, v22
	v_cvt_pk_bf16_f32 v38, v65, v38
	v_cvt_pk_bf16_f32 v39, v67, v39
	ds_write_b128 v76, v[36:39] offset:18432
	v_cndmask_b32_e32 v59, v62, v59, vcc
	v_div_scale_f32 v62, s[0:1], v59, v59, 1.0
	v_rcp_f32_e32 v63, v62
	v_lshlrev_b32_e32 v39, 16, v34
	v_and_b32_e32 v34, 0xffff0000, v34
	v_fma_f32 v36, -v62, v63, 1.0
	v_fmac_f32_e32 v63, v36, v63
	v_div_scale_f32 v36, vcc, 1.0, v59, 1.0
	v_mul_f32_e32 v37, v36, v63
	v_fma_f32 v38, -v62, v37, v36
	v_fmac_f32_e32 v37, v38, v63
	v_fma_f32 v36, -v62, v37, v36
	v_div_fmas_f32 v36, v36, v63, v37
	v_lshlrev_b32_e32 v37, 16, v32
	v_div_fixup_f32 v36, v36, v59, 1.0
	v_sub_f32_e32 v37, v37, v58
	v_mul_f32_e32 v37, v37, v36
	v_fma_f32 v24, v28, v37, v24
	v_sub_f32_e32 v28, v39, v58
	v_and_b32_e32 v32, 0xffff0000, v32
	v_mul_f32_e32 v28, v28, v36
	v_fma_f32 v20, v16, v28, v20
	v_sub_f32_e32 v16, v32, v58
	v_mul_f32_e32 v16, v16, v36
	v_fma_f32 v16, v29, v16, v25
	v_sub_f32_e32 v25, v34, v58
	v_lshlrev_b32_e32 v59, 16, v35
	v_mul_f32_e32 v25, v25, v36
	v_fma_f32 v21, v17, v25, v21
	v_sub_f32_e32 v25, v59, v58
	v_lshlrev_b32_e32 v38, 16, v33
	v_and_b32_e32 v33, 0xffff0000, v33
	v_mul_f32_e32 v25, v25, v36
	v_fma_f32 v22, v18, v25, v22
	v_sub_f32_e32 v18, v33, v58
	v_and_b32_e32 v35, 0xffff0000, v35
	v_sub_f32_e32 v17, v38, v58
	v_mul_f32_e32 v18, v18, v36
	v_mul_f32_e32 v17, v17, v36
	v_fmac_f32_e32 v27, v31, v18
	v_sub_f32_e32 v18, v35, v58
	v_fma_f32 v17, v30, v17, v26
	v_mul_f32_e32 v18, v18, v36
	v_cvt_pk_bf16_f32 v16, v24, v16
	v_fmac_f32_e32 v23, v19, v18
	v_cvt_pk_bf16_f32 v17, v17, v27
	v_cvt_pk_bf16_f32 v18, v20, v21
	v_cvt_pk_bf16_f32 v19, v22, v23
	ds_write_b128 v76, v[16:19] offset:27648
	v_bfe_u32 v16, v41, 2, 2
	v_or_b32_e32 v16, v162, v16
	v_and_b32_e32 v17, 24, v77
	v_mul_u32_u24_e32 v16, 0x120, v16
	v_add3_u32 v41, s75, v17, v16
	s_xor_b32 s75, s75, 0x10000
	s_mov_b32 s76, 0
	s_nop 0
	s_waitcnt lgkmcnt(0)
	s_barrier
	v_mov_b32_e32 v252, v41
	ds_read_b64_tr_b16 v[110:111], v252 offset:32
	ds_read_b64_tr_b16 v[112:113], v252 offset:1184
	ds_read_b64_tr_b16 v[114:115], v252
	ds_read_b64_tr_b16 v[116:117], v252 offset:1152
	ds_read_b64_tr_b16 v[118:119], v252 offset:9248
	ds_read_b64_tr_b16 v[120:121], v252 offset:10400
	ds_read_b64_tr_b16 v[122:123], v252 offset:9216
	ds_read_b64_tr_b16 v[124:125], v252 offset:10368
	ds_read_b64_tr_b16 v[126:127], v252 offset:18464
	ds_read_b64_tr_b16 v[128:129], v252 offset:19616
	ds_read_b64_tr_b16 v[130:131], v252 offset:18432
	ds_read_b64_tr_b16 v[132:133], v252 offset:19584
	s_waitcnt vmcnt(3)
	s_waitcnt lgkmcnt(10)
	v_mfma_f32_16x16x32_bf16 v[24:27], v[110:113], v[0:3], 0
	ds_read_b64_tr_b16 v[134:135], v252 offset:27680
	ds_read_b64_tr_b16 v[136:137], v252 offset:28832
	s_waitcnt lgkmcnt(10)
	v_mfma_f32_16x16x32_bf16 v[16:19], v[114:117], v[0:3], 0
	ds_read_b64_tr_b16 v[138:139], v252 offset:64
	ds_read_b64_tr_b16 v[140:141], v252 offset:1216
	s_waitcnt vmcnt(2)
	s_waitcnt lgkmcnt(10)
	v_mfma_f32_16x16x32_bf16 v[24:27], v[118:121], v[4:7], v[24:27]
	ds_read_b64_tr_b16 v[142:143], v252 offset:96
	ds_read_b64_tr_b16 v[144:145], v252 offset:1248
	s_waitcnt lgkmcnt(10)
	v_mfma_f32_16x16x32_bf16 v[16:19], v[122:125], v[4:7], v[16:19]
	ds_read_b64_tr_b16 v[146:147], v252 offset:27648
	ds_read_b64_tr_b16 v[148:149], v252 offset:28800
	s_waitcnt vmcnt(1)
	s_waitcnt lgkmcnt(10)
	v_mfma_f32_16x16x32_bf16 v[24:27], v[126:129], v[12:15], v[24:27]
	ds_read_b64_tr_b16 v[150:151], v252 offset:9280
	ds_read_b64_tr_b16 v[152:153], v252 offset:10432
	s_waitcnt lgkmcnt(10)
	v_mfma_f32_16x16x32_bf16 v[16:19], v[130:133], v[12:15], v[16:19]
	ds_read_b64_tr_b16 v[154:155], v252 offset:9312
	ds_read_b64_tr_b16 v[156:157], v252 offset:10464
	s_waitcnt vmcnt(0)
	s_waitcnt lgkmcnt(10)
	v_mfma_f32_16x16x32_bf16 v[20:23], v[134:137], v[8:11], v[24:27]
	ds_read_b64_tr_b16 v[172:173], v252 offset:160
	ds_read_b64_tr_b16 v[174:175], v252 offset:1312
	s_waitcnt lgkmcnt(10)
	v_mfma_f32_16x16x32_bf16 v[24:27], v[138:141], v[0:3], 0
	ds_read_b64_tr_b16 v[176:177], v252 offset:18496
	ds_read_b64_tr_b16 v[178:179], v252 offset:19648
	s_waitcnt lgkmcnt(10)
	v_mfma_f32_16x16x32_bf16 v[28:31], v[142:145], v[0:3], 0
	ds_read_b64_tr_b16 v[180:181], v252 offset:18528
	ds_read_b64_tr_b16 v[182:183], v252 offset:19680
	s_waitcnt lgkmcnt(10)
	v_mfma_f32_16x16x32_bf16 v[16:19], v[146:149], v[8:11], v[16:19]
	ds_read_b64_tr_b16 v[184:185], v252 offset:128
	ds_read_b64_tr_b16 v[186:187], v252 offset:1280
	s_waitcnt lgkmcnt(10)
	v_mfma_f32_16x16x32_bf16 v[24:27], v[150:153], v[4:7], v[24:27]
	ds_read_b64_tr_b16 v[188:189], v252 offset:9376
	ds_read_b64_tr_b16 v[190:191], v252 offset:10528
	s_waitcnt lgkmcnt(10)
	v_mfma_f32_16x16x32_bf16 v[28:31], v[154:157], v[4:7], v[28:31]
	ds_read_b64_tr_b16 v[192:193], v252 offset:27712
	ds_read_b64_tr_b16 v[194:195], v252 offset:28864
	s_waitcnt lgkmcnt(10)
; #define LAS __attribute__((address_space(3)))
; __device__ __forceinline__ void gmlp_unit(const bf16* proj, unsigned char* ws, LAS unsigned char* lds, int gu) {
;     ...
;     for (int ct = 0; ct < 8; ++ct) {
;         acc[ct] = (f32x4){0.f, 0.f, 0.f, 0.f};
; #pragma unroll
;         for (int s = 0; s < 4; ++s) {
;             const LAS unsigned char* p0 = VN + (32 * s + 8 * fq + (fr >> 2)) * V_STRIDE + (16 * ct + 4 * (fr & 3)) * 2;
;             const bf16x8 vf = tr_frag(p0, p0 + 4 * V_STRIDE);
;             acc[ct] = __builtin_amdgcn_mfma_f32_16x16x32_bf16(vf, wf[s], acc[ct], 0, 0, 0);
;         }
;     }
	v_mfma_f32_16x16x32_bf16 v[62:65], v[172:175], v[0:3], 0
	ds_read_b64_tr_b16 v[196:197], v252 offset:27744
	ds_read_b64_tr_b16 v[198:199], v252 offset:28896
	s_waitcnt lgkmcnt(10)
	v_mfma_f32_16x16x32_bf16 v[24:27], v[176:179], v[12:15], v[24:27]
	ds_read_b64_tr_b16 v[200:201], v252 offset:9344
	ds_read_b64_tr_b16 v[202:203], v252 offset:10496
	s_waitcnt lgkmcnt(10)
	v_mfma_f32_16x16x32_bf16 v[28:31], v[180:183], v[12:15], v[28:31]
	ds_read_b64_tr_b16 v[204:205], v252 offset:18592
	ds_read_b64_tr_b16 v[206:207], v252 offset:19744
	s_waitcnt lgkmcnt(10)
	v_mfma_f32_16x16x32_bf16 v[32:35], v[184:187], v[0:3], 0
	ds_read_b64_tr_b16 v[208:209], v252 offset:18560
	ds_read_b64_tr_b16 v[210:211], v252 offset:19712
	s_waitcnt lgkmcnt(10)
	v_mfma_f32_16x16x32_bf16 v[62:65], v[188:191], v[4:7], v[62:65]
	ds_read_b64_tr_b16 v[212:213], v252 offset:27808
	ds_read_b64_tr_b16 v[214:215], v252 offset:28960
	s_waitcnt lgkmcnt(10)
	v_mfma_f32_16x16x32_bf16 v[24:27], v[192:195], v[8:11], v[24:27]
	ds_read_b64_tr_b16 v[216:217], v252 offset:192
	ds_read_b64_tr_b16 v[218:219], v252 offset:1344
	s_waitcnt lgkmcnt(10)
	v_mfma_f32_16x16x32_bf16 v[28:31], v[196:199], v[8:11], v[28:31]
	ds_read_b64_tr_b16 v[220:221], v252 offset:224
	ds_read_b64_tr_b16 v[222:223], v252 offset:1376
	s_waitcnt lgkmcnt(10)
	v_mfma_f32_16x16x32_bf16 v[32:35], v[200:203], v[4:7], v[32:35]
	ds_read_b64_tr_b16 v[224:225], v252 offset:9408
	ds_read_b64_tr_b16 v[226:227], v252 offset:10560
	s_waitcnt lgkmcnt(10)
	v_mfma_f32_16x16x32_bf16 v[62:65], v[204:207], v[12:15], v[62:65]
	ds_read_b64_tr_b16 v[228:229], v252 offset:9440
	ds_read_b64_tr_b16 v[230:231], v252 offset:10592
	s_waitcnt lgkmcnt(10)
	v_mfma_f32_16x16x32_bf16 v[32:35], v[208:211], v[12:15], v[32:35]
	ds_read_b64_tr_b16 v[232:233], v252 offset:18624
	ds_read_b64_tr_b16 v[234:235], v252 offset:19776
	v_ashrrev_i32_e32 v41, 31, v40
	s_waitcnt lgkmcnt(10)
	v_mfma_f32_16x16x32_bf16 v[36:39], v[212:215], v[8:11], v[62:65]
	ds_read_b64_tr_b16 v[236:237], v252 offset:18656
	ds_read_b64_tr_b16 v[238:239], v252 offset:19808
	s_waitcnt lgkmcnt(10)
	v_mfma_f32_16x16x32_bf16 v[62:65], v[216:219], v[0:3], 0
	ds_read_b64_tr_b16 v[240:241], v252 offset:27776
	ds_read_b64_tr_b16 v[242:243], v252 offset:28928
	s_waitcnt lgkmcnt(10)
	v_mfma_f32_16x16x32_bf16 v[0:3], v[220:223], v[0:3], 0
	ds_read_b64_tr_b16 v[244:245], v252 offset:27840
	ds_read_b64_tr_b16 v[246:247], v252 offset:28992
	s_waitcnt lgkmcnt(10)
	v_mfma_f32_16x16x32_bf16 v[62:65], v[224:227], v[4:7], v[62:65]
	ds_read_b64_tr_b16 v[248:249], v252 offset:27872
	ds_read_b64_tr_b16 v[250:251], v252 offset:29024
	s_waitcnt lgkmcnt(10)
	v_mfma_f32_16x16x32_bf16 v[0:3], v[228:231], v[4:7], v[0:3]
	v_lshlrev_b64 v[4:5], 12, v[40:41]
	v_lshl_add_u64 v[4:5], s[28:29], 0, v[4:5]
	v_lshl_add_u64 v[4:5], v[4:5], 0, s[44:45]
	s_waitcnt lgkmcnt(8)
	v_mfma_f32_16x16x32_bf16 v[62:65], v[232:235], v[12:15], v[62:65]
	v_lshl_add_u64 v[4:5], v[4:5], 0, v[162:163]
	v_lshl_add_u64 v[6:7], v[4:5], 0, s[48:49]
	v_add_co_u32_e32 v4, vcc, s63, v4
	s_waitcnt lgkmcnt(6)
	v_mfma_f32_16x16x32_bf16 v[0:3], v[236:239], v[12:15], v[0:3]
	v_add_f32_e32 v12, v61, v19
	v_addc_co_u32_e32 v5, vcc, 0, v5, vcc
	s_waitcnt lgkmcnt(4)
	v_mfma_f32_16x16x32_bf16 v[32:35], v[240:243], v[8:11], v[32:35]
	v_cmp_lt_i32_e32 vcc, v168, v169
	s_waitcnt lgkmcnt(2)
	v_mfma_f32_16x16x32_bf16 v[62:65], v[244:247], v[8:11], v[62:65]
	s_waitcnt lgkmcnt(0)
; __device__ __forceinline__ unsigned pk2(float lo, float hi) { return pg8::cvt_pk_bf16(lo, hi); }
; __device__ __forceinline__ void gmlp_unit(const bf16* proj, unsigned char* ws, LAS unsigned char* lds, int gu) {
;     ...
;     float ss = 0.f;
; #pragma unroll
;     for (int ct = 0; ct < 8; ++ct) {
;         const float o0 = bflo(uw[ct].x) * (acc[ct][0] + bsp), o1 = bfhi(uw[ct].x) * (acc[ct][1] + bsp), o2 = bflo(uw[ct].y) * (acc[ct][2] + bsp), o3 = bfhi(uw[ct].y) * (acc[ct][3] + bsp);
;         ss += (o0 * o0 + o1 * o1) + (o2 * o2 + o3 * o3);
;         v2u w; w.x = pk2(o0, o1); w.y = pk2(o2, o3); *(v2u*)(orow + 16 * ct) = w;
;     }
;     ss += __shfl_xor(ss, 16); ss += __shfl_xor(ss, 32);
;     if (fq == 0) unsafeAtomicAdd(ssmix + (size_t)tok * 2 + 1, ss);
	v_mfma_f32_16x16x32_bf16 v[0:3], v[248:251], v[8:11], v[0:3]
	v_lshlrev_b32_e32 v8, 16, v56
	v_add_f32_e32 v9, v61, v16
	v_mul_f32_e32 v8, v9, v8
	v_and_b32_e32 v9, 0xffff0000, v56
	v_add_f32_e32 v10, v61, v17
	v_mul_f32_e32 v9, v10, v9
	v_lshlrev_b32_e32 v10, 16, v57
	v_add_f32_e32 v11, v61, v18
	v_mul_f32_e32 v10, v11, v10
	v_and_b32_e32 v11, 0xffff0000, v57
	v_mul_f32_e32 v11, v12, v11
	v_mul_f32_e32 v12, v9, v9
	v_fmac_f32_e32 v12, v8, v8
	v_cvt_pk_bf16_f32 v8, v8, v9
	v_cvt_pk_bf16_f32 v9, v10, v11
	global_store_dwordx2 v[4:5], v[8:9], off offset:2048
	v_lshlrev_b32_e32 v4, 16, v54
	v_add_f32_e32 v5, v61, v20
	v_mul_f32_e32 v4, v5, v4
	v_and_b32_e32 v5, 0xffff0000, v54
	v_add_f32_e32 v8, v61, v21
	v_mul_f32_e32 v13, v11, v11
	v_mul_f32_e32 v5, v8, v5
	v_lshlrev_b32_e32 v8, 16, v55
	v_add_f32_e32 v9, v61, v22
	v_fmac_f32_e32 v13, v10, v10
	v_mul_f32_e32 v8, v9, v8
	v_and_b32_e32 v9, 0xffff0000, v55
	v_add_f32_e32 v10, v61, v23
	v_mul_f32_e32 v9, v10, v9
	v_mul_f32_e32 v10, v5, v5
	v_fmac_f32_e32 v10, v4, v4
	v_cvt_pk_bf16_f32 v4, v4, v5
	v_cvt_pk_bf16_f32 v5, v8, v9
	v_mul_f32_e32 v11, v9, v9
	global_store_dwordx2 v[6:7], v[4:5], off offset:32
	v_lshlrev_b32_e32 v4, 16, v52
	v_add_f32_e32 v5, v61, v24
	v_fmac_f32_e32 v11, v8, v8
	v_mul_f32_e32 v4, v5, v4
	v_and_b32_e32 v5, 0xffff0000, v52
	v_add_f32_e32 v8, v61, v25
	v_mul_f32_e32 v5, v8, v5
	v_lshlrev_b32_e32 v8, 16, v53
	v_add_f32_e32 v9, v61, v26
	v_add_f32_e32 v10, v10, v11
	v_mul_f32_e32 v8, v9, v8
	v_and_b32_e32 v9, 0xffff0000, v53
	v_add_f32_e32 v11, v61, v27
	v_mul_f32_e32 v9, v11, v9
	v_mul_f32_e32 v11, v5, v5
	v_add_f32_e32 v12, v12, v13
	v_fmac_f32_e32 v11, v4, v4
	v_cvt_pk_bf16_f32 v4, v4, v5
	v_cvt_pk_bf16_f32 v5, v8, v9
	v_add_f32_e32 v10, v12, v10
	v_mul_f32_e32 v12, v9, v9
	global_store_dwordx2 v[6:7], v[4:5], off offset:64
	v_lshlrev_b32_e32 v4, 16, v50
	v_add_f32_e32 v5, v61, v28
	v_fmac_f32_e32 v12, v8, v8
	v_mul_f32_e32 v4, v5, v4
	v_and_b32_e32 v5, 0xffff0000, v50
	v_add_f32_e32 v8, v61, v29
	v_add_f32_e32 v11, v11, v12
	v_mul_f32_e32 v5, v8, v5
	v_lshlrev_b32_e32 v8, 16, v51
	v_add_f32_e32 v9, v61, v30
	v_add_f32_e32 v10, v10, v11
	v_mul_f32_e32 v8, v9, v8
	v_and_b32_e32 v9, 0xffff0000, v51
	v_add_f32_e32 v11, v61, v31
	v_mul_f32_e32 v9, v11, v9
	v_mul_f32_e32 v11, v5, v5
	v_fmac_f32_e32 v11, v4, v4
	v_cvt_pk_bf16_f32 v4, v4, v5
	v_cvt_pk_bf16_f32 v5, v8, v9
	v_mul_f32_e32 v12, v9, v9
	global_store_dwordx2 v[6:7], v[4:5], off offset:96
	v_lshlrev_b32_e32 v4, 16, v48
	v_add_f32_e32 v5, v61, v32
	v_fmac_f32_e32 v12, v8, v8
	v_mul_f32_e32 v4, v5, v4
	v_and_b32_e32 v5, 0xffff0000, v48
	v_add_f32_e32 v8, v61, v33
	v_add_f32_e32 v11, v11, v12
	v_mul_f32_e32 v5, v8, v5
	v_lshlrev_b32_e32 v8, 16, v49
	v_add_f32_e32 v9, v61, v34
	v_add_f32_e32 v10, v10, v11
	v_mul_f32_e32 v8, v9, v8
	v_and_b32_e32 v9, 0xffff0000, v49
	v_add_f32_e32 v11, v61, v35
	v_mul_f32_e32 v9, v11, v9
	v_mul_f32_e32 v11, v5, v5
	v_fmac_f32_e32 v11, v4, v4
	v_cvt_pk_bf16_f32 v4, v4, v5
	v_cvt_pk_bf16_f32 v5, v8, v9
	v_mul_f32_e32 v12, v9, v9
	global_store_dwordx2 v[6:7], v[4:5], off offset:128
	v_lshlrev_b32_e32 v4, 16, v46
	v_add_f32_e32 v5, v61, v36
	v_fmac_f32_e32 v12, v8, v8
	v_mul_f32_e32 v4, v5, v4
	v_and_b32_e32 v5, 0xffff0000, v46
	v_add_f32_e32 v8, v61, v37
	v_add_f32_e32 v11, v11, v12
	v_mul_f32_e32 v5, v8, v5
	v_lshlrev_b32_e32 v8, 16, v47
	v_add_f32_e32 v9, v61, v38
	v_add_f32_e32 v10, v10, v11
	v_mul_f32_e32 v8, v9, v8
	v_and_b32_e32 v9, 0xffff0000, v47
	v_add_f32_e32 v11, v61, v39
	v_mul_f32_e32 v9, v11, v9
	v_mul_f32_e32 v11, v5, v5
	v_mul_f32_e32 v12, v9, v9
	v_fmac_f32_e32 v11, v4, v4
	v_fmac_f32_e32 v12, v8, v8
	v_add_f32_e32 v11, v11, v12
	v_cvt_pk_bf16_f32 v4, v4, v5
	v_cvt_pk_bf16_f32 v5, v8, v9
	v_lshlrev_b32_e32 v8, 16, v44
	v_add_f32_e32 v9, v61, v62
	v_add_f32_e32 v10, v10, v11
	v_mul_f32_e32 v8, v9, v8
	v_and_b32_e32 v9, 0xffff0000, v44
	v_add_f32_e32 v11, v61, v63
	v_mul_f32_e32 v9, v11, v9
	v_lshlrev_b32_e32 v11, 16, v45
	v_add_f32_e32 v12, v61, v64
	v_mul_f32_e32 v11, v12, v11
	v_and_b32_e32 v12, 0xffff0000, v45
	v_add_f32_e32 v13, v61, v65
	v_mul_f32_e32 v12, v13, v12
	v_mul_f32_e32 v13, v9, v9
	v_mul_f32_e32 v14, v12, v12
	v_fmac_f32_e32 v13, v8, v8
	v_fmac_f32_e32 v14, v11, v11
	v_add_f32_e32 v13, v13, v14
	v_add_f32_e32 v10, v10, v13
	v_lshlrev_b32_e32 v13, 16, v42
	v_add_f32_e32 v0, v61, v0
	v_mul_f32_e32 v13, v0, v13
	v_and_b32_e32 v0, 0xffff0000, v42
	v_add_f32_e32 v1, v61, v1
	v_mul_f32_e32 v14, v1, v0
	v_lshlrev_b32_e32 v0, 16, v43
	v_add_f32_e32 v1, v61, v2
	v_mul_f32_e32 v15, v1, v0
	v_and_b32_e32 v0, 0xffff0000, v43
	v_add_f32_e32 v1, v61, v3
	v_mul_f32_e32 v3, v1, v0
	v_mul_f32_e32 v0, v14, v14
	v_mul_f32_e32 v1, v3, v3
	v_fmac_f32_e32 v0, v13, v13
	v_fmac_f32_e32 v1, v15, v15
	v_add_f32_e32 v0, v0, v1
	v_add_f32_e32 v2, v10, v0
	v_cndmask_b32_e32 v0, v167, v168, vcc
	v_lshlrev_b32_e32 v0, 2, v0
	ds_bpermute_b32 v10, v0, v2
	global_store_dwordx2 v[6:7], v[4:5], off offset:160
	v_cvt_pk_bf16_f32 v0, v8, v9
	v_cvt_pk_bf16_f32 v1, v11, v12
	v_cmp_lt_i32_e32 vcc, v170, v169
	global_store_dwordx2 v[6:7], v[0:1], off offset:192
	s_waitcnt lgkmcnt(0)
	v_add_f32_e32 v0, v2, v10
	v_cndmask_b32_e32 v1, v167, v170, vcc
	v_lshlrev_b32_e32 v1, 2, v1
	ds_bpermute_b32 v1, v1, v0
	v_cmp_eq_u32_e32 vcc, 0, v60
	v_cvt_pk_bf16_f32 v2, v13, v14
	v_cvt_pk_bf16_f32 v3, v15, v3
	global_store_dwordx2 v[6:7], v[2:3], off offset:224
	s_and_saveexec_b64 s[2:3], vcc
	s_cbranch_execz .LBB0_602
	s_waitcnt lgkmcnt(0)
	v_add_f32_e32 v2, v0, v1
	v_lshl_add_u64 v[0:1], v[40:41], 3, s[28:29]
	v_add_co_u32_e32 v0, vcc, 0x40000, v0
	s_nop 1
	v_addc_co_u32_e32 v1, vcc, 0, v1, vcc
	global_atomic_add_f32 v[0:1], v2, off offset:4
